# up-GEMM loop: in the first K-iteration after an epilogue the first two waits allow the 16 epilogue stores to stay in flight
# speedup vs baseline: 1.0013x; 1.0013x over previous
; #define PG8_STAGE(bufoff, gbase, voff) do { _Pragma("unroll") for (int _i = 0; _i < 2; ++_i) \
;         __builtin_amdgcn_global_load_lds((const unsigned*)((const char*)(gbase) + (voff)[_i]), (LAS unsigned*)(lds + (bufoff) + ldsw + _i * 8192), 16, 0, 0); } while (0)
; #define PG8_LDA(dst, b, h) do { _Pragma("unroll") for (int m = 0; m < NM; ++m) _Pragma("unroll") for (int k = 0; k < 2; ++k) dst[m][k] = *(const LAS bf16x8*)(lds + PG8_SA(b, h) + aoff + m * 2048 + k * 1024); } while (0)
; #define PG8_LDB(dst, b, h) do { _Pragma("unroll") for (int n = 0; n < 2; ++n) _Pragma("unroll") for (int k = 0; k < 2; ++k) dst[n][k] = *(const LAS bf16x8*)(lds + PG8_SB(b, h) + boff + n * 2048 + k * 1024); } while (0)
; #define PG8_MMA(ai, bj, At, Bt) do { __builtin_amdgcn_s_setprio(1); _Pragma("unroll") for (int m = 0; m < NM; ++m) _Pragma("unroll") for (int n = 0; n < 2; ++n) _Pragma("unroll") for (int k = 0; k < 2; ++k) \
;         acc[ai][bj][m][n] = __builtin_amdgcn_mfma_f32_16x16x32_bf16(Bt[n][k], At[m][k], acc[ai][bj][m][n], 0, 0, 0); __builtin_amdgcn_s_setprio(0); } while (0)
; #define PG8_WAIT_V(n) asm volatile("s_waitcnt vmcnt(" #n ")" ::: "memory")
; #define PG8_WAIT_L(n) asm volatile("s_waitcnt lgkmcnt(" #n ")" ::: "memory")
; #define PG8_BAR __builtin_amdgcn_s_barrier()
; #define PG8_SCHED __builtin_amdgcn_sched_barrier(0)
;     ...
;             PG8_LDB(B0, 0, 0); PG8_LDB(B1, 0, 1); PG8_SCHED; PG8_LDA(At, 0, 0); PG8_STAGE(PG8_SA(1, 1), a1 + hstepA, voffA);
;             PG8_WAIT_V(8); PG8_WAIT_L(0); PG8_BAR; PG8_MMA(0, 0, At, B0); PG8_MMA(0, 1, At, B1); PG8_BAR; PG8_SCHED;
;             PG8_LDA(At, 0, 1); PG8_STAGE(PG8_SB(0, 0), b2, voffB); PG8_STAGE(PG8_SB(0, 1), b2 + hstepB, voffB); PG8_STAGE(PG8_SA(0, 0), a2, voffA);
;             PG8_WAIT_V(8); PG8_WAIT_L(0); PG8_BAR; PG8_MMA(1, 0, At, B0); PG8_MMA(1, 1, At, B1); PG8_BAR; PG8_SCHED;
.LBB0_1783:
	v_add_u32_e32 v0, s64, v208
	ds_read_b128 v[130:133], v0
	ds_read_b128 v[134:137], v0 offset:1024
	ds_read_b128 v[138:141], v0 offset:2048
	ds_read_b128 v[142:145], v0 offset:3072
	v_add_u32_e32 v0, s70, v208
	ds_read_b128 v[146:149], v0
	ds_read_b128 v[150:153], v0 offset:1024
	ds_read_b128 v[154:157], v0 offset:2048
	ds_read_b128 v[158:161], v0 offset:3072
	s_add_u32 s14, s12, 0xfff80080
	s_addc_u32 s15, s13, -1
	s_cmp_eq_u32 vcc_lo, 28
	s_cselect_b32 s47, s2, s15
	s_cselect_b32 s46, s3, s14
	s_cselect_b32 s15, s9, s41
	s_cselect_b32 s14, s11, s37
	s_cselect_b32 s100, -1, 0
	s_andn2_b32 s100, s100, s101
	s_add_i32 m0, s73, 0xc000
	ds_read_b128 v[162:165], v209
	ds_read_b128 v[166:169], v209 offset:1024
	ds_read_b128 v[170:173], v209 offset:2048
	ds_read_b128 v[174:177], v209 offset:3072
	ds_read_b128 v[190:193], v209 offset:4096
	ds_read_b128 v[194:197], v209 offset:5120
	ds_read_b128 v[198:201], v209 offset:6144
	ds_read_b128 v[202:205], v209 offset:7168
	global_load_lds_dwordx4 v186, s[12:13]
	s_add_i32 m0, s73, 0xe000
	s_nop 0
	global_load_lds_dwordx4 v188, s[12:13]
	s_cmp_eq_u32 vcc_lo, 0
	s_cbranch_scc0 .Lfi_up0n
	s_cmp_gt_u32 s78, 1
	s_cbranch_scc0 .Lfi_up0n
	s_waitcnt vmcnt(24)
	s_branch .Lfi_up0d
.Lfi_up0n:
	s_waitcnt vmcnt(8)
.Lfi_up0d:
	s_waitcnt lgkmcnt(0)
	s_barrier
	s_setprio 1
	s_waitcnt lgkmcnt(0)
	v_mfma_f32_16x16x32_bf16 v[126:129], v[130:133], v[162:165], v[126:129]
	v_mfma_f32_16x16x32_bf16 v[94:97], v[138:141], v[162:165], v[94:97]
	v_mfma_f32_16x16x32_bf16 v[110:113], v[130:133], v[170:173], v[110:113]
	v_mfma_f32_16x16x32_bf16 v[70:73], v[138:141], v[170:173], v[70:73]
	v_mfma_f32_16x16x32_bf16 v[106:109], v[130:133], v[190:193], v[106:109]
	v_mfma_f32_16x16x32_bf16 v[66:69], v[138:141], v[190:193], v[66:69]
	v_mfma_f32_16x16x32_bf16 v[118:121], v[130:133], v[198:201], v[118:121]
	v_mfma_f32_16x16x32_bf16 v[86:89], v[138:141], v[198:201], v[86:89]
	v_mfma_f32_16x16x32_bf16 v[126:129], v[134:137], v[166:169], v[126:129]
	v_mfma_f32_16x16x32_bf16 v[94:97], v[142:145], v[166:169], v[94:97]
	v_mfma_f32_16x16x32_bf16 v[110:113], v[134:137], v[174:177], v[110:113]
	v_mfma_f32_16x16x32_bf16 v[70:73], v[142:145], v[174:177], v[70:73]
	v_mfma_f32_16x16x32_bf16 v[106:109], v[134:137], v[194:197], v[106:109]
	v_mfma_f32_16x16x32_bf16 v[66:69], v[142:145], v[194:197], v[66:69]
	v_mfma_f32_16x16x32_bf16 v[118:121], v[134:137], v[202:205], v[118:121]
	v_mfma_f32_16x16x32_bf16 v[86:89], v[142:145], v[202:205], v[86:89]
	s_setprio 0
	s_setprio 1
	v_mfma_f32_16x16x32_bf16 v[122:125], v[146:149], v[162:165], v[122:125]
	v_mfma_f32_16x16x32_bf16 v[90:93], v[154:157], v[162:165], v[90:93]
	v_mfma_f32_16x16x32_bf16 v[102:105], v[146:149], v[170:173], v[102:105]
	v_mfma_f32_16x16x32_bf16 v[62:65], v[154:157], v[170:173], v[62:65]
	v_mfma_f32_16x16x32_bf16 v[98:101], v[146:149], v[190:193], v[98:101]
	v_mfma_f32_16x16x32_bf16 v[58:61], v[154:157], v[190:193], v[58:61]
	v_mfma_f32_16x16x32_bf16 v[114:117], v[146:149], v[198:201], v[114:117]
	v_mfma_f32_16x16x32_bf16 v[82:85], v[154:157], v[198:201], v[82:85]
	v_mfma_f32_16x16x32_bf16 v[122:125], v[150:153], v[166:169], v[122:125]
	v_mfma_f32_16x16x32_bf16 v[90:93], v[158:161], v[166:169], v[90:93]
	v_mfma_f32_16x16x32_bf16 v[102:105], v[150:153], v[174:177], v[102:105]
	v_mfma_f32_16x16x32_bf16 v[62:65], v[158:161], v[174:177], v[62:65]
	v_mfma_f32_16x16x32_bf16 v[98:101], v[150:153], v[194:197], v[98:101]
	v_mfma_f32_16x16x32_bf16 v[58:61], v[158:161], v[194:197], v[58:61]
	v_mfma_f32_16x16x32_bf16 v[114:117], v[150:153], v[202:205], v[114:117]
	v_mfma_f32_16x16x32_bf16 v[82:85], v[158:161], v[202:205], v[82:85]
	s_setprio 0
	s_barrier
	s_mov_b32 m0, s68
	s_add_u32 s22, s14, 0x80000
	s_addc_u32 s23, s15, 0
	ds_read_b128 v[162:165], v209 offset:16384
	ds_read_b128 v[166:169], v209 offset:17408
	ds_read_b128 v[170:173], v209 offset:18432
	ds_read_b128 v[174:177], v209 offset:19456
	ds_read_b128 v[190:193], v209 offset:20480
	ds_read_b128 v[194:197], v209 offset:21504
	ds_read_b128 v[198:201], v209 offset:22528
	ds_read_b128 v[202:205], v209 offset:23552
	s_cmp_lg_u32 s100, 0
	s_cbranch_scc1 .Ltl_up_0s
	global_load_lds_dwordx4 v180, s[14:15]
	s_mov_b32 m0, s69
	s_nop 0
	global_load_lds_dwordx4 v184, s[14:15]
	s_mov_b32 m0, s71
	s_nop 0
	global_load_lds_dwordx4 v180, s[22:23]
	s_mov_b32 m0, s72
	s_nop 0
	global_load_lds_dwordx4 v184, s[22:23]
	s_mov_b32 m0, s73
	s_nop 0
	global_load_lds_dwordx4 v178, s[46:47]
	s_mov_b32 m0, s74
	s_nop 0
	global_load_lds_dwordx4 v182, s[46:47]
	s_cmp_eq_u32 vcc_lo, 0
	s_cbranch_scc0 .Lfi_up1n
	s_cmp_gt_u32 s78, 1
	s_cbranch_scc0 .Lfi_up1n
	s_waitcnt vmcnt(24)
	s_branch .Lfi_up1d
